# HID 32-col slab layout (no deferred stores) with sc1 nt on the P8 stores
# speedup vs baseline: 1.0020x; 1.0020x over previous
.LBB0_880:
	v_lshl_add_u32 v150, s34, 8, v144
	v_lshl_or_b32 v152, s56, 8, v146
	v_ashrrev_i32_e32 v151, 31, v150
	v_max_f32_e32 v124, 0, v124
	v_max_f32_e32 v120, 0, v120
	v_max_f32_e32 v125, 0, v125
	v_max_f32_e32 v121, 0, v121
	v_max_f32_e32 v126, 0, v126
	v_max_f32_e32 v127, 0, v127
	v_ashrrev_i32_e32 v153, 31, v152
	v_lshlrev_b64 v[154:155], 6, v[150:151]
	v_pk_mul_f32 v[124:125], v[124:125], v[124:125]
	v_pk_mul_f32 v[120:121], v[120:121], v[120:121]
	v_max_f32_e32 v122, 0, v122
	v_max_f32_e32 v123, 0, v123
	v_pk_mul_f32 v[126:127], v[126:127], v[126:127]
	v_pk_mul_f32 v[156:157], v[122:123], v[122:123]
	v_cvt_pk_bf16_f32 v122, v124, v125
	v_cvt_pk_bf16_f32 v123, v126, v127
	v_cvt_pk_bf16_f32 v124, v120, v121
	v_lshl_add_u64 v[120:121], s[78:79], 0, v[154:155]
	v_and_b32_e32 v126, 0xfe0, v152
	v_and_b32_e32 v127, 31, v152
	v_lshlrev_b32_e32 v126, 16, v126
	v_lshl_or_b32 v126, v127, 1, v126
	v_mov_b32_e32 v127, 0
	v_cvt_pk_bf16_f32 v125, v156, v157
	v_lshl_add_u64 v[120:121], v[120:121], 0, v[126:127]
	v_max_f32_e32 v112, 0, v112
	v_max_f32_e32 v113, 0, v113
	global_store_dwordx4 v[120:121], v[122:125], off sc1 nt
	s_nop 1
	v_pk_mul_f32 v[122:123], v[112:113], v[112:113]
	v_max_f32_e32 v114, 0, v114
	v_max_f32_e32 v116, 0, v116
	v_max_f32_e32 v117, 0, v117
	v_max_f32_e32 v112, 0, v118
	v_max_f32_e32 v113, 0, v119
	v_max_f32_e32 v115, 0, v115
	v_pk_mul_f32 v[116:117], v[116:117], v[116:117]
	v_pk_mul_f32 v[118:119], v[112:113], v[112:113]
	v_pk_mul_f32 v[124:125], v[114:115], v[114:115]
	v_cvt_pk_bf16_f32 v112, v116, v117
	v_cvt_pk_bf16_f32 v113, v118, v119
	v_cvt_pk_bf16_f32 v114, v122, v123
	v_cvt_pk_bf16_f32 v115, v124, v125
	v_max_f32_e32 v104, 0, v104
	v_max_f32_e32 v105, 0, v105
	v_lshl_add_u64 v[200:201], v[120:121], 0, s[98:99]
	global_store_dwordx4 v[200:201], v[112:115], off sc1 nt
	s_nop 1
	v_or_b32_e32 v112, 16, v150
	v_pk_mul_f32 v[114:115], v[104:105], v[104:105]
	v_ashrrev_i32_e32 v113, 31, v112
	v_max_f32_e32 v108, 0, v108
	v_max_f32_e32 v109, 0, v109
	v_max_f32_e32 v106, 0, v106
	v_lshlrev_b64 v[112:113], 6, v[112:113]
	v_pk_mul_f32 v[108:109], v[108:109], v[108:109]
	v_max_f32_e32 v104, 0, v110
	v_max_f32_e32 v105, 0, v111
	v_max_f32_e32 v107, 0, v107
	v_pk_mul_f32 v[110:111], v[104:105], v[104:105]
	v_pk_mul_f32 v[116:117], v[106:107], v[106:107]
	v_cvt_pk_bf16_f32 v104, v108, v109
	v_lshl_add_u64 v[108:109], s[78:79], 0, v[112:113]
	v_cvt_pk_bf16_f32 v105, v110, v111
	v_cvt_pk_bf16_f32 v106, v114, v115
	v_cvt_pk_bf16_f32 v107, v116, v117
	v_lshl_add_u64 v[108:109], v[108:109], 0, v[126:127]
	v_max_f32_e32 v96, 0, v96
	v_max_f32_e32 v97, 0, v97
	global_store_dwordx4 v[108:109], v[104:107], off sc1 nt
	s_nop 1
	v_pk_mul_f32 v[104:105], v[96:97], v[96:97]
	v_max_f32_e32 v98, 0, v98
	v_max_f32_e32 v100, 0, v100
	v_max_f32_e32 v101, 0, v101
	v_max_f32_e32 v96, 0, v102
	v_max_f32_e32 v97, 0, v103
	v_max_f32_e32 v99, 0, v99
	v_pk_mul_f32 v[100:101], v[100:101], v[100:101]
	v_pk_mul_f32 v[102:103], v[96:97], v[96:97]
	v_pk_mul_f32 v[106:107], v[98:99], v[98:99]
	v_cvt_pk_bf16_f32 v96, v100, v101
	v_cvt_pk_bf16_f32 v97, v102, v103
	v_cvt_pk_bf16_f32 v98, v104, v105
	v_cvt_pk_bf16_f32 v99, v106, v107
	v_max_f32_e32 v88, 0, v88
	v_max_f32_e32 v89, 0, v89
	v_lshl_add_u64 v[202:203], v[108:109], 0, s[98:99]
	global_store_dwordx4 v[202:203], v[96:99], off sc1 nt
	s_nop 1
	v_or_b32_e32 v96, 32, v150
	v_pk_mul_f32 v[98:99], v[88:89], v[88:89]
	v_ashrrev_i32_e32 v97, 31, v96
	v_max_f32_e32 v92, 0, v92
	v_max_f32_e32 v93, 0, v93
	v_max_f32_e32 v90, 0, v90
	v_lshlrev_b64 v[96:97], 6, v[96:97]
	v_pk_mul_f32 v[92:93], v[92:93], v[92:93]
	v_max_f32_e32 v88, 0, v94
	v_max_f32_e32 v89, 0, v95
	v_max_f32_e32 v91, 0, v91
	v_pk_mul_f32 v[94:95], v[88:89], v[88:89]
	v_pk_mul_f32 v[100:101], v[90:91], v[90:91]
	v_cvt_pk_bf16_f32 v88, v92, v93
	v_lshl_add_u64 v[92:93], s[78:79], 0, v[96:97]
	v_cvt_pk_bf16_f32 v89, v94, v95
	v_cvt_pk_bf16_f32 v90, v98, v99
	v_cvt_pk_bf16_f32 v91, v100, v101
	v_lshl_add_u64 v[92:93], v[92:93], 0, v[126:127]
	v_max_f32_e32 v80, 0, v80
	v_max_f32_e32 v81, 0, v81
	global_store_dwordx4 v[92:93], v[88:91], off sc1 nt
	s_nop 1
	v_pk_mul_f32 v[88:89], v[80:81], v[80:81]
	v_max_f32_e32 v82, 0, v82
	v_max_f32_e32 v84, 0, v84
	v_max_f32_e32 v85, 0, v85
	v_max_f32_e32 v80, 0, v86
	v_max_f32_e32 v81, 0, v87
	v_max_f32_e32 v83, 0, v83
	v_pk_mul_f32 v[84:85], v[84:85], v[84:85]
	v_pk_mul_f32 v[86:87], v[80:81], v[80:81]
	v_pk_mul_f32 v[90:91], v[82:83], v[82:83]
	v_cvt_pk_bf16_f32 v80, v84, v85
	v_cvt_pk_bf16_f32 v81, v86, v87
	v_cvt_pk_bf16_f32 v82, v88, v89
	v_cvt_pk_bf16_f32 v83, v90, v91
	v_max_f32_e32 v72, 0, v72
	v_max_f32_e32 v73, 0, v73
	v_lshl_add_u64 v[204:205], v[92:93], 0, s[98:99]
	global_store_dwordx4 v[204:205], v[80:83], off sc1 nt
	s_nop 1
	v_or_b32_e32 v80, 48, v150
	v_pk_mul_f32 v[82:83], v[72:73], v[72:73]
	v_ashrrev_i32_e32 v81, 31, v80
	v_max_f32_e32 v76, 0, v76
	v_max_f32_e32 v77, 0, v77
	v_max_f32_e32 v74, 0, v74
	v_lshlrev_b64 v[80:81], 6, v[80:81]
	v_pk_mul_f32 v[76:77], v[76:77], v[76:77]
	v_max_f32_e32 v72, 0, v78
	v_max_f32_e32 v73, 0, v79
	v_max_f32_e32 v75, 0, v75
	v_pk_mul_f32 v[78:79], v[72:73], v[72:73]
	v_pk_mul_f32 v[84:85], v[74:75], v[74:75]
	v_cvt_pk_bf16_f32 v72, v76, v77
	v_lshl_add_u64 v[76:77], s[78:79], 0, v[80:81]
	v_cvt_pk_bf16_f32 v73, v78, v79
	v_cvt_pk_bf16_f32 v74, v82, v83
	v_cvt_pk_bf16_f32 v75, v84, v85
	v_lshl_add_u64 v[76:77], v[76:77], 0, v[126:127]
	v_max_f32_e32 v64, 0, v64
	v_max_f32_e32 v65, 0, v65
	global_store_dwordx4 v[76:77], v[72:75], off sc1 nt
	s_nop 1
	v_pk_mul_f32 v[72:73], v[64:65], v[64:65]
	v_max_f32_e32 v66, 0, v66
	v_max_f32_e32 v68, 0, v68
	v_max_f32_e32 v69, 0, v69
	v_max_f32_e32 v64, 0, v70
	v_max_f32_e32 v65, 0, v71
	v_max_f32_e32 v67, 0, v67
	v_pk_mul_f32 v[68:69], v[68:69], v[68:69]
	v_pk_mul_f32 v[70:71], v[64:65], v[64:65]
	v_pk_mul_f32 v[74:75], v[66:67], v[66:67]
	v_cvt_pk_bf16_f32 v64, v68, v69
	v_cvt_pk_bf16_f32 v65, v70, v71
	v_cvt_pk_bf16_f32 v66, v72, v73
	v_cvt_pk_bf16_f32 v67, v74, v75
	v_max_f32_e32 v56, 0, v56
	v_max_f32_e32 v57, 0, v57
	v_lshl_add_u64 v[206:207], v[76:77], 0, s[98:99]
	global_store_dwordx4 v[206:207], v[64:67], off sc1 nt
	s_nop 1
	v_pk_mul_f32 v[64:65], v[56:57], v[56:57]
	v_max_f32_e32 v58, 0, v58
	v_max_f32_e32 v56, 0, v62
	v_max_f32_e32 v57, 0, v63
	v_max_f32_e32 v60, 0, v60
	v_max_f32_e32 v61, 0, v61
	v_max_f32_e32 v59, 0, v59
	v_pk_mul_f32 v[62:63], v[56:57], v[56:57]
	v_pk_mul_f32 v[60:61], v[60:61], v[60:61]
	v_pk_mul_f32 v[66:67], v[58:59], v[58:59]
	v_cvt_pk_bf16_f32 v57, v62, v63
	v_add_co_u32_e32 v62, vcc, s52, v120
	v_cvt_pk_bf16_f32 v56, v60, v61
	v_cvt_pk_bf16_f32 v58, v64, v65
	v_cvt_pk_bf16_f32 v59, v66, v67
	v_addc_co_u32_e32 v63, vcc, 0, v121, vcc
	v_max_f32_e32 v48, 0, v48
	v_max_f32_e32 v49, 0, v49
	global_store_dwordx4 v[62:63], v[56:59], off sc1 nt
	s_nop 1
	v_pk_mul_f32 v[56:57], v[48:49], v[48:49]
	v_max_f32_e32 v50, 0, v50
	v_max_f32_e32 v52, 0, v52
	v_max_f32_e32 v53, 0, v53
	v_max_f32_e32 v48, 0, v54
	v_max_f32_e32 v49, 0, v55
	v_max_f32_e32 v51, 0, v51
	v_pk_mul_f32 v[52:53], v[52:53], v[52:53]
	v_pk_mul_f32 v[54:55], v[48:49], v[48:49]
	v_pk_mul_f32 v[58:59], v[50:51], v[50:51]
	v_lshl_add_u64 v[60:61], v[120:121], 0, s[16:17]
	v_cvt_pk_bf16_f32 v48, v52, v53
	v_cvt_pk_bf16_f32 v49, v54, v55
	v_cvt_pk_bf16_f32 v50, v56, v57
	v_cvt_pk_bf16_f32 v51, v58, v59
	v_max_f32_e32 v40, 0, v40
	v_max_f32_e32 v41, 0, v41
	global_store_dwordx4 v[60:61], v[48:51], off sc1 nt
	s_nop 1
	v_pk_mul_f32 v[48:49], v[40:41], v[40:41]
	v_max_f32_e32 v42, 0, v42
	v_max_f32_e32 v40, 0, v46
	v_max_f32_e32 v41, 0, v47
	v_max_f32_e32 v44, 0, v44
	v_max_f32_e32 v45, 0, v45
	v_max_f32_e32 v43, 0, v43
	v_pk_mul_f32 v[46:47], v[40:41], v[40:41]
	v_pk_mul_f32 v[44:45], v[44:45], v[44:45]
	v_pk_mul_f32 v[50:51], v[42:43], v[42:43]
	v_cvt_pk_bf16_f32 v41, v46, v47
	v_add_co_u32_e32 v46, vcc, s53, v120
	v_cvt_pk_bf16_f32 v40, v44, v45
	v_cvt_pk_bf16_f32 v42, v48, v49
	v_cvt_pk_bf16_f32 v43, v50, v51
	v_addc_co_u32_e32 v47, vcc, 0, v121, vcc
	v_max_f32_e32 v32, 0, v32
	v_max_f32_e32 v33, 0, v33
	global_store_dwordx4 v[46:47], v[40:43], off sc1 nt
	s_nop 1
	v_pk_mul_f32 v[40:41], v[32:33], v[32:33]
	v_max_f32_e32 v34, 0, v34
	v_max_f32_e32 v36, 0, v36
	v_max_f32_e32 v37, 0, v37
	v_max_f32_e32 v32, 0, v38
	v_max_f32_e32 v33, 0, v39
	v_max_f32_e32 v35, 0, v35
	v_pk_mul_f32 v[36:37], v[36:37], v[36:37]
	v_pk_mul_f32 v[38:39], v[32:33], v[32:33]
	v_pk_mul_f32 v[42:43], v[34:35], v[34:35]
	v_lshl_add_u64 v[44:45], v[120:121], 0, s[18:19]
	v_cvt_pk_bf16_f32 v32, v36, v37
	v_cvt_pk_bf16_f32 v33, v38, v39
	v_cvt_pk_bf16_f32 v34, v40, v41
	v_cvt_pk_bf16_f32 v35, v42, v43
	v_max_f32_e32 v24, 0, v24
	v_max_f32_e32 v25, 0, v25
	global_store_dwordx4 v[44:45], v[32:35], off sc1 nt
	s_nop 1
	v_pk_mul_f32 v[32:33], v[24:25], v[24:25]
	v_max_f32_e32 v26, 0, v26
	v_max_f32_e32 v24, 0, v30
	v_max_f32_e32 v25, 0, v31
	v_max_f32_e32 v28, 0, v28
	v_max_f32_e32 v29, 0, v29
	v_max_f32_e32 v27, 0, v27
	v_pk_mul_f32 v[30:31], v[24:25], v[24:25]
	v_pk_mul_f32 v[28:29], v[28:29], v[28:29]
	v_pk_mul_f32 v[34:35], v[26:27], v[26:27]
	v_cvt_pk_bf16_f32 v25, v30, v31
	v_add_co_u32_e32 v30, vcc, s54, v120
	v_cvt_pk_bf16_f32 v24, v28, v29
	v_cvt_pk_bf16_f32 v26, v32, v33
	v_cvt_pk_bf16_f32 v27, v34, v35
	v_addc_co_u32_e32 v31, vcc, 0, v121, vcc
	v_max_f32_e32 v16, 0, v16
	v_max_f32_e32 v17, 0, v17
	global_store_dwordx4 v[30:31], v[24:27], off sc1 nt
	s_nop 1
	v_pk_mul_f32 v[24:25], v[16:17], v[16:17]
	v_max_f32_e32 v18, 0, v18
	v_max_f32_e32 v20, 0, v20
	v_max_f32_e32 v21, 0, v21
	v_max_f32_e32 v16, 0, v22
	v_max_f32_e32 v17, 0, v23
	v_max_f32_e32 v19, 0, v19
	v_pk_mul_f32 v[20:21], v[20:21], v[20:21]
	v_pk_mul_f32 v[22:23], v[16:17], v[16:17]
	v_pk_mul_f32 v[26:27], v[18:19], v[18:19]
	v_lshl_add_u64 v[28:29], v[120:121], 0, s[20:21]
	v_cvt_pk_bf16_f32 v16, v20, v21
	v_cvt_pk_bf16_f32 v17, v22, v23
	v_cvt_pk_bf16_f32 v18, v24, v25
	v_cvt_pk_bf16_f32 v19, v26, v27
	v_max_f32_e32 v8, 0, v8
	v_max_f32_e32 v9, 0, v9
	global_store_dwordx4 v[28:29], v[16:19], off sc1 nt
	s_nop 1
	v_pk_mul_f32 v[16:17], v[8:9], v[8:9]
	v_max_f32_e32 v10, 0, v10
	v_max_f32_e32 v8, 0, v14
	v_max_f32_e32 v9, 0, v15
	v_max_f32_e32 v12, 0, v12
	v_max_f32_e32 v13, 0, v13
	v_max_f32_e32 v11, 0, v11
	v_pk_mul_f32 v[14:15], v[8:9], v[8:9]
	v_pk_mul_f32 v[12:13], v[12:13], v[12:13]
	v_pk_mul_f32 v[18:19], v[10:11], v[10:11]
	v_cvt_pk_bf16_f32 v9, v14, v15
	v_add_co_u32_e32 v14, vcc, s55, v120
	v_cvt_pk_bf16_f32 v8, v12, v13
	v_cvt_pk_bf16_f32 v10, v16, v17
	v_cvt_pk_bf16_f32 v11, v18, v19
	v_addc_co_u32_e32 v15, vcc, 0, v121, vcc
	v_max_f32_e32 v0, 0, v0
	v_max_f32_e32 v1, 0, v1
	global_store_dwordx4 v[14:15], v[8:11], off sc1 nt
	s_nop 1
	v_pk_mul_f32 v[8:9], v[0:1], v[0:1]
	v_max_f32_e32 v2, 0, v2
	v_max_f32_e32 v4, 0, v4
	v_max_f32_e32 v5, 0, v5
	v_max_f32_e32 v0, 0, v6
	v_max_f32_e32 v1, 0, v7
	v_max_f32_e32 v3, 0, v3
	v_pk_mul_f32 v[4:5], v[4:5], v[4:5]
	v_pk_mul_f32 v[6:7], v[0:1], v[0:1]
	v_pk_mul_f32 v[10:11], v[2:3], v[2:3]
	v_lshl_add_u64 v[12:13], v[120:121], 0, s[22:23]
	v_cvt_pk_bf16_f32 v0, v4, v5
	v_cvt_pk_bf16_f32 v1, v6, v7
	v_cvt_pk_bf16_f32 v2, v8, v9
	v_cvt_pk_bf16_f32 v3, v10, v11
	s_andn2_b64 vcc, exec, s[4:5]
	s_mov_b64 s[4:5], -1
	global_store_dwordx4 v[12:13], v[0:3], off sc1 nt
	s_cbranch_vccnz .LBB0_869
	s_andn2_b64 vcc, exec, s[6:7]
	s_cbranch_vccnz .LBB0_868
	s_barrier
	s_branch .LBB0_868
